# attention softplus: identity range fix-ups of log removed (bit-identical); per-wave early stop; gate loads in flight together
# baseline (speedup 1.0000x reference)
; #define LAS __attribute__((address_space(3)))
; __device__ __forceinline__ void attn_phase(Frame& F, bf16* OZ) {
;     ...
;     for (int u = blockIdx.x; u < 2048 + 512; u += F.G) {
;         const bool smp = u >= 2048; const int us = u - 2048;
;         const int h = smp ? (us & 15) : (u & 15), qb = u >> 4, b = us >> 4;
;         const int qrow0 = smp ? SEQ + b * 16 : qb * 128, nq = smp ? 16 : 128;
; #pragma unroll
;         for (int i = 0; i < 4; ++i) { const int idx = tid + i * NTHREADS, t = idx >> 4, c8 = (idx & 15) * 8; v4u v = (v4u){0u, 0u, 0u, 0u};
;             if (t < nq) v = *(const v4u*)(Qb + (size_t)(qrow0 + t) * D + h * 128 + c8);
;             *(LAS v4u*)(L + QS + t * ST_ + c8 * 2) = v; }
;         const int nkb = smp ? 17 : 2 * qb + 2;
;         ATT_LOAD_KV(0);
.LBB0_1881:
	s_mov_b64 s[64:65], 0
	s_cmpk_lt_i32 s57, 0x800
	s_cselect_b64 s[0:1], -1, 0
	s_add_i32 s61, s57, 0xfffff800
	s_ashr_i32 s19, s57, 4
	s_and_b32 s20, s61, -16
	s_and_b32 s58, s57, 15
	s_addk_i32 s20, 0x4000
	s_lshl_b32 s60, s19, 7
	s_cmpk_gt_i32 s57, 0x7ff
	s_cselect_b64 s[38:39], -1, 0
	s_and_b64 s[2:3], s[38:39], exec
	s_cselect_b32 s18, 16, 0x80
	s_cselect_b32 s59, s20, s60
	s_lshl_b32 s36, s58, 8
	v_lshl_add_u64 v[4:5], v[76:77], 0, s[36:37]
	v_cmp_gt_u32_e32 vcc, s18, v82
	v_mov_b32_e32 v10, 0
	v_mov_b32_e32 v11, 0
	v_mov_b32_e32 v12, 0
	v_mov_b32_e32 v13, 0
	s_and_saveexec_b64 s[2:3], vcc
	s_cbranch_execz .LBB0_1883
	v_add_u32_e32 v10, s59, v82
	v_ashrrev_i32_e32 v11, 31, v10
	v_lshlrev_b64 v[10:11], 12, v[10:11]
	v_lshl_add_u64 v[10:11], v[4:5], 0, v[10:11]
	global_load_dwordx4 v[10:13], v[10:11], off

; #define LAS __attribute__((address_space(3)))
; #define MFMA16(a, b, c) __builtin_amdgcn_mfma_f32_16x16x32_bf16((a), (b), (c), 0, 0, 0)
; __device__ __forceinline__ void attn_phase(Frame& F, bf16* OZ) {
;     ...
;         for (int kb = 0; kb < nkb; ++kb) {
;             const int spos0 = !smp ? (2 * qb + 1 - kb) * 64 : (kb == 0 ? 1024 : 1024 - 64 * kb), nvalid = (smp && kb == 0) ? 16 : 64;
;             if (kb > 0) { ATT_LOAD_KV(kb); __syncthreads(); }
;             bool done = true;
;             const bool none_visible = spos0 > __builtin_amdgcn_readfirstlane(tpos - l15) + 14;
;             if (active && none_visible) done = false;
;             if (active && !none_visible) {
;                 f32x4 sc[4];
; #pragma unroll
;                 for (int sb = 0; sb < 4; ++sb) { sc[sb] = (f32x4){0.f, 0.f, 0.f, 0.f};
; #pragma unroll
;                     for (int ks = 0; ks < 4; ++ks) { const bf16x8 a = *(const LAS bf16x8*)(L + KS + (16 * sb + l15) * ST_ + (32 * ks + 8 * g4) * 2); sc[sb] = MFMA16(a, qf[ks], sc[sb]); } }
;                 float lk[4][4], tsum[4], above[4], ttot[4];
; #pragma unroll
;                 for (int sb = 0; sb < 4; ++sb) { tsum[sb] = 0.f;
; #pragma unroll
;                     for (int e = 0; e < 4; ++e) { const int s = 16 * sb + 4 * g4 + e; const float z = sc[sb][e]; const bool vis = (s < nvalid) && (spos0 + s < tpos);
;                         const float sp = fmaxf(z, 0.f) + __logf(1.0f + __expf(-fabsf(z)));
;                         lk[sb][e] = vis ? -sp : 0.f; sc[sb][e] = vis ? z - sp : -1e30f; tsum[sb] += lk[sb][e]; }
.LBB0_1895:
	s_lshl_b32 s1, s19, 1
	s_add_i32 s19, s1, 2
	s_and_b64 s[2:3], s[38:39], exec
	s_cselect_b32 s36, 17, s19
	s_cmp_lt_u32 s33, s18
	s_cselect_b64 s[40:41], -1, 0
	s_cmp_lt_i32 s36, 1
	s_waitcnt vmcnt(0)
	ds_write_b128 v145, v[10:13] offset:52224
	s_waitcnt lgkmcnt(0)
	s_barrier
	s_cbranch_scc1 .LBB0_1898
	v_add_u32_e32 v90, s0, v87
	s_lshl_b32 s0, s1, 6
	s_xor_b64 s[42:43], s[40:41], -1
	s_or_b32 s2, s0, 64
	ds_read_b128 v[10:13], v143
	ds_read_b128 v[14:17], v143 offset:64
	ds_read_b128 v[18:21], v143 offset:128
	ds_read_b128 v[22:25], v143 offset:192
	v_sub_u32_e32 v150, v90, v83
	s_and_b64 s[0:1], s[38:39], exec
	v_readfirstlane_b32 s0, v150
	s_cselect_b32 s2, 0x400, s2
	s_add_i32 s0, s0, 14
	s_cmp_gt_i32 s2, s0
	s_cselect_b64 s[0:1], -1, 0
	s_or_b64 s[18:19], s[42:43], s[0:1]
	s_and_b64 vcc, exec, s[18:19]
	s_cbranch_vccnz .LBB0_1899
	ds_read_b128 v[26:29], v146 offset:34816
	ds_read_b128 v[30:33], v146 offset:34880
	ds_read_b128 v[34:37], v146 offset:39168
	ds_read_b128 v[38:41], v146 offset:39232
	ds_read_b128 v[42:45], v146 offset:34944
	v_and_b32_e32 v4, 64, v147
	s_waitcnt lgkmcnt(4)
	v_mfma_f32_16x16x32_bf16 v[26:29], v[26:29], v[10:13], 0
	v_xor_b32_e32 v3, 16, v147
	v_add_u32_e32 v4, 64, v4
	v_cmp_lt_i32_e32 vcc, v3, v4
	s_waitcnt lgkmcnt(3)
	v_mfma_f32_16x16x32_bf16 v[26:29], v[30:33], v[14:17], v[26:29]
	ds_read_b128 v[30:33], v146 offset:35008
	v_cndmask_b32_e32 v3, v147, v3, vcc
	v_lshlrev_b32_e32 v47, 2, v3
	s_waitcnt lgkmcnt(1)
	v_mfma_f32_16x16x32_bf16 v[26:29], v[42:45], v[18:21], v[26:29]
	ds_read_b128 v[42:45], v146 offset:39296
	v_xor_b32_e32 v3, 32, v147
	v_cmp_lt_i32_e32 vcc, v3, v4
	v_mfma_f32_16x16x32_bf16 v[34:37], v[34:37], v[10:13], 0
	s_and_b64 s[0:1], s[38:39], exec
	v_cndmask_b32_e32 v3, v147, v3, vcc
	v_lshlrev_b32_e32 v46, 2, v3
	s_waitcnt lgkmcnt(1)
	v_mfma_f32_16x16x32_bf16 v[30:33], v[30:33], v[22:25], v[26:29]
	v_xor_b32_e32 v3, 48, v147
	v_cmp_lt_i32_e32 vcc, v3, v4
	s_cselect_b32 s3, 16, 64
	ds_read_b128 v[26:29], v146 offset:39360
	v_mfma_f32_16x16x32_bf16 v[34:37], v[38:41], v[14:17], v[34:37]
	ds_read_b128 v[38:41], v146 offset:43520
	ds_read_b128 v[48:51], v146 offset:43584
	ds_read_b128 v[52:55], v146 offset:43648
	ds_read_b128 v[56:59], v146 offset:43712
	v_mul_f32_e64 v4, |v30|, s49
	v_exp_f32_e32 v4, v4
	s_waitcnt lgkmcnt(5)
	v_mfma_f32_16x16x32_bf16 v[34:37], v[42:45], v[18:21], v[34:37]
	v_cndmask_b32_e32 v3, v147, v3, vcc
	ds_read_b128 v[42:45], v146 offset:47872
	ds_read_b128 v[60:63], v146 offset:47936
	ds_read_b128 v[64:67], v146 offset:48000
	ds_read_b128 v[68:71], v146 offset:48064
	v_add_f32_e32 v4, 1.0, v4
	s_waitcnt lgkmcnt(8)
	v_mfma_f32_16x16x32_bf16 v[26:29], v[26:29], v[22:25], v[34:37]
	s_waitcnt lgkmcnt(7)
	v_mfma_f32_16x16x32_bf16 v[34:37], v[38:41], v[10:13], 0
	v_log_f32_e32 v4, v4
	s_waitcnt lgkmcnt(6)
	v_mfma_f32_16x16x32_bf16 v[34:37], v[48:51], v[14:17], v[34:37]
	v_max_f32_e32 v5, v30, v30
	v_max_f32_e32 v5, 0, v5
	s_waitcnt lgkmcnt(5)
	v_mfma_f32_16x16x32_bf16 v[34:37], v[52:55], v[18:21], v[34:37]
	v_lshlrev_b32_e32 v48, 2, v3
	v_or_b32_e32 v3, s2, v86
	s_waitcnt lgkmcnt(4)
	v_mfma_f32_16x16x32_bf16 v[38:41], v[56:59], v[22:25], v[34:37]
	s_waitcnt lgkmcnt(3)
	v_mfma_f32_16x16x32_bf16 v[34:37], v[42:45], v[10:13], 0
	v_mul_f32_e32 v42, 0x3f317217, v4
	v_fma_f32 v42, v4, s53, -v42
	v_fmac_f32_e32 v42, 0x3377d1cf, v4
	v_fma_f32 v4, v4, s53, v42
	v_add_f32_e32 v4, v5, v4
	v_sub_f32_e32 v5, v30, v4
	v_mul_f32_e64 v30, |v31|, s49
	v_exp_f32_e32 v30, v30
	v_sub_f32_e32 v50, 0, v4
	v_cmp_lt_i32_e32 vcc, v3, v90
	v_mul_f32_e64 v43, |v33|, s49
	v_add_f32_e32 v4, 1.0, v30
	v_cndmask_b32_e32 v3, v149, v5, vcc
	v_max_f32_e32 v30, v31, v31
	v_log_f32_e32 v4, v4
	v_max_f32_e32 v30, 0, v30
	v_or_b32_e32 v5, s2, v98
	v_exp_f32_e32 v43, v43
	v_mul_f32_e32 v42, 0x3f317217, v4
	v_fma_f32 v42, v4, s53, -v42
	v_fmac_f32_e32 v42, 0x3377d1cf, v4
	v_fma_f32 v4, v4, s53, v42
	v_mul_f32_e64 v52, |v38|, s49
	v_exp_f32_e32 v52, v52
	v_add_f32_e32 v30, v30, v4
	v_mul_f32_e64 v4, |v32|, s49
	v_exp_f32_e32 v42, v4
	v_cmp_lt_i32_e64 s[0:1], v5, v90
	v_sub_f32_e32 v5, v31, v30
	v_add_f32_e32 v52, 1.0, v52
	v_cndmask_b32_e64 v49, v149, v5, s[0:1]
	v_add_f32_e32 v5, 1.0, v42
	v_cndmask_b32_e64 v4, 0, -v30, s[0:1]
	s_waitcnt lgkmcnt(2)
	v_mfma_f32_16x16x32_bf16 v[34:37], v[60:63], v[14:17], v[34:37]
	v_or_b32_e32 v31, s2, v88
	v_log_f32_e32 v5, v5
	v_max_f32_e32 v30, v32, v32
	v_max_f32_e32 v42, 0, v30
	s_waitcnt lgkmcnt(1)
	v_mfma_f32_16x16x32_bf16 v[34:37], v[64:67], v[18:21], v[34:37]
	v_mul_f32_e32 v30, 0x3f317217, v5
	v_fma_f32 v30, v5, s53, -v30
	v_fmac_f32_e32 v30, 0x3377d1cf, v5
	v_fma_f32 v5, v5, s53, v30
	s_waitcnt lgkmcnt(0)
; __device__ __forceinline__ void attn_phase(Frame& F, bf16* OZ) {
;     ...
;                 for (int sb = 0; sb < 4; ++sb) { tsum[sb] = 0.f;
; #pragma unroll
;                     for (int e = 0; e < 4; ++e) { const int s = 16 * sb + 4 * g4 + e; const float z = sc[sb][e]; const bool vis = (s < nvalid) && (spos0 + s < tpos);
;                         const float sp = fmaxf(z, 0.f) + __logf(1.0f + __expf(-fabsf(z)));
;                         lk[sb][e] = vis ? -sp : 0.f; sc[sb][e] = vis ? z - sp : -1e30f; tsum[sb] += lk[sb][e]; }
;                     const float v1 = __shfl_xor(tsum[sb], 16), v2 = __shfl_xor(tsum[sb], 32), v3 = __shfl_xor(tsum[sb], 48);
;                     above[sb] = ((g4 ^ 1) > g4 ? v1 : 0.f) + ((g4 ^ 2) > g4 ? v2 : 0.f) + ((g4 ^ 3) > g4 ? v3 : 0.f);
;                     ttot[sb] = (tsum[sb] + v1) + (v2 + v3); }
	v_mfma_f32_16x16x32_bf16 v[34:37], v[68:71], v[22:25], v[34:37]
	v_mov_b32_e32 v44, v5
	v_add_f32_e32 v5, 1.0, v43
	v_max_f32_e32 v43, v33, v33
	v_max_f32_e32 v43, 0, v43
	v_log_f32_e32 v5, v5
	v_or_b32_e32 v30, s2, v99
	v_mul_f32_e32 v45, 0x3f317217, v5
	v_fma_f32 v45, v5, s53, -v45
	v_fmac_f32_e32 v45, 0x3377d1cf, v5
	v_fma_f32 v5, v5, s53, v45
	s_nop 1
	v_add_f32_e32 v5, v43, v5
	v_cmp_lt_i32_e64 s[0:1], v30, v90
	s_nop 1
	v_cndmask_b32_e64 v30, 0, -v5, s[0:1]
	v_sub_f32_e32 v5, v33, v5
	v_mul_f32_e64 v33, |v26|, s49
	v_exp_f32_e32 v43, v33
	v_cndmask_b32_e64 v33, v149, v5, s[0:1]
	v_or_b32_e32 v5, s2, v100
	v_cmp_lt_i32_e64 s[20:21], v5, v90
	v_add_f32_e32 v43, 1.0, v43
	v_max_f32_e32 v5, v26, v26
	v_max_f32_e32 v5, 0, v5
	v_log_f32_e32 v43, v43
	v_cmp_gt_u32_e64 s[0:1], s3, v100
	s_and_b64 s[0:1], s[0:1], s[20:21]
	v_mul_f32_e32 v45, 0x3f317217, v43
	v_fma_f32 v45, v43, s53, -v45
	v_fmac_f32_e32 v45, 0x3377d1cf, v43
	v_fma_f32 v43, v43, s53, v45
	s_nop 1
	v_add_f32_e32 v5, v5, v43
	v_mul_f32_e64 v43, |v27|, s49
	v_exp_f32_e32 v43, v43
	v_or_b32_e32 v45, s2, v101
	v_sub_f32_e32 v26, v26, v5
	v_sub_f32_e32 v5, 0, v5
	v_add_f32_e32 v43, 1.0, v43
	v_cmp_lt_i32_e64 s[20:21], v45, v90
	v_max_f32_e32 v45, v27, v27
	v_log_f32_e32 v43, v43
	v_cndmask_b32_e64 v26, v149, v26, s[0:1]
	v_cndmask_b32_e64 v5, 0, v5, s[0:1]
	v_cmp_gt_u32_e64 s[0:1], s3, v101
	v_mul_f32_e32 v51, 0x3f317217, v43
	v_fma_f32 v51, v43, s53, -v51
	v_fmac_f32_e32 v51, 0x3377d1cf, v43
	v_fma_f32 v43, v43, s53, v51
	v_max_f32_e32 v45, 0, v45
	s_and_b64 s[0:1], s[0:1], s[20:21]
	v_add_f32_e32 v43, v45, v43
	v_cndmask_b32_e64 v58, 0, -v43, s[0:1]
	v_sub_f32_e32 v27, v27, v43
	v_mul_f32_e64 v43, |v28|, s49
	v_exp_f32_e32 v43, v43
	v_or_b32_e32 v45, s2, v1
	v_cmp_lt_i32_e64 s[20:21], v45, v90
	v_max_f32_e32 v45, v28, v28
	v_add_f32_e32 v43, 1.0, v43
	v_max_f32_e32 v45, 0, v45
	v_cndmask_b32_e64 v27, v149, v27, s[0:1]
	v_log_f32_e32 v43, v43
	v_cmp_gt_u32_e64 s[0:1], s3, v1
	v_add_f32_e32 v5, v58, v5
	v_mul_f32_e32 v51, 0x3f317217, v43
	v_fma_f32 v51, v43, s53, -v51
	v_fmac_f32_e32 v51, 0x3377d1cf, v43
	v_fma_f32 v43, v43, s53, v51
	s_nop 1
	v_add_f32_e32 v51, v45, v43
	v_mul_f32_e64 v43, |v29|, s49
	v_exp_f32_e32 v43, v43
	v_sub_f32_e32 v28, v28, v51
	s_and_b64 s[18:19], s[0:1], s[20:21]
	v_cndmask_b32_e64 v59, v149, v28, s[18:19]
	v_add_f32_e32 v43, 1.0, v43
	v_cmp_gt_f32_e64 s[22:23], s52, v43
	v_or_b32_e32 v28, s2, v75
	v_cmp_lt_i32_e64 s[20:21], v28, v90
	v_cndmask_b32_e64 v45, 0, 32, s[22:23]
	v_ldexp_f32 v43, v43, v45
	v_log_f32_e32 v45, v43
	v_max_f32_e32 v28, v29, v29
	v_max_f32_e32 v43, 0, v28
	v_cmp_gt_u32_e64 s[0:1], s3, v75
	v_mul_f32_e32 v28, 0x3f317217, v45
	v_fma_f32 v28, v45, s53, -v28
	v_fmac_f32_e32 v28, 0x3377d1cf, v45
	v_fmac_f32_e32 v28, 0x3f317217, v45
	v_cmp_lt_f32_e64 s[24:25], |v45|, s54
	s_nop 1
	v_cndmask_b32_e64 v28, v45, v28, s[24:25]
	v_cndmask_b32_e64 v45, 0, v148, s[22:23]
	v_sub_f32_e32 v45, v28, v45
	v_log_f32_e32 v52, v52
	v_or_b32_e32 v28, s2, v102
	v_cmp_lt_i32_e64 s[26:27], v28, v90
	v_max_f32_e32 v28, v38, v38
	v_mul_f32_e32 v53, 0x3f317217, v52
	v_fma_f32 v53, v52, s53, -v53
	v_fmac_f32_e32 v53, 0x3377d1cf, v52
	v_fma_f32 v52, v52, s53, v53
	v_max_f32_e32 v28, 0, v28
	v_cmp_gt_u32_e64 s[22:23], s3, v102
	v_add_f32_e32 v28, v28, v52
	v_sub_f32_e32 v38, v38, v28
	s_and_b64 s[22:23], s[22:23], s[26:27]
	v_cndmask_b32_e64 v66, v149, v38, s[22:23]
	v_mul_f32_e64 v38, |v39|, s49
	v_exp_f32_e32 v38, v38
	v_or_b32_e32 v52, s2, v103
	v_sub_f32_e32 v28, 0, v28
	v_cmp_lt_i32_e64 s[26:27], v52, v90
	v_add_f32_e32 v38, 1.0, v38
	v_max_f32_e32 v52, v39, v39
	v_cndmask_b32_e64 v28, 0, v28, s[22:23]
	v_log_f32_e32 v38, v38
	v_cmp_gt_u32_e64 s[22:23], s3, v103
	v_max_f32_e32 v52, 0, v52
	s_and_b64 s[22:23], s[22:23], s[26:27]
	v_mul_f32_e32 v53, 0x3f317217, v38
	v_fma_f32 v53, v38, s53, -v53
	v_fmac_f32_e32 v53, 0x3377d1cf, v38
	v_fma_f32 v38, v38, s53, v53
	s_nop 1
	v_add_f32_e32 v38, v52, v38
	v_cndmask_b32_e64 v67, 0, -v38, s[22:23]
	v_sub_f32_e32 v38, v39, v38
	v_cndmask_b32_e64 v62, v149, v38, s[22:23]
	v_mul_f32_e64 v38, |v40|, s49
	v_exp_f32_e32 v38, v38
	v_or_b32_e32 v39, s2, v104
	v_cmp_lt_i32_e64 s[26:27], v39, v90
	v_max_f32_e32 v39, v40, v40
	v_add_f32_e32 v38, 1.0, v38
	v_cmp_gt_u32_e64 s[22:23], s3, v104
	v_max_f32_e32 v39, 0, v39
	v_log_f32_e32 v38, v38
	s_and_b64 s[22:23], s[22:23], s[26:27]
	v_add_f32_e32 v28, v67, v28
	v_mul_f32_e32 v52, 0x3f317217, v38
	v_fma_f32 v52, v38, s53, -v52
	v_fmac_f32_e32 v52, 0x3377d1cf, v38
	v_fma_f32 v38, v38, s53, v52
	s_nop 1
	v_add_f32_e32 v38, v39, v38
	v_cndmask_b32_e64 v60, 0, -v38, s[22:23]
	v_sub_f32_e32 v38, v40, v38
	v_cndmask_b32_e64 v61, v149, v38, s[22:23]
	v_mul_f32_e64 v38, |v41|, s49
	v_exp_f32_e32 v38, v38
	v_or_b32_e32 v39, s2, v105
	v_cmp_lt_i32_e64 s[26:27], v39, v90
	v_max_f32_e32 v39, v41, v41
	v_add_f32_e32 v38, 1.0, v38
	v_cmp_gt_u32_e64 s[22:23], s3, v105
	v_max_f32_e32 v39, 0, v39
	v_log_f32_e32 v38, v38
	s_and_b64 s[22:23], s[22:23], s[26:27]
	v_add_f32_e32 v28, v60, v28
	v_mul_f32_e32 v40, 0x3f317217, v38
	v_fma_f32 v40, v38, s53, -v40
	v_fmac_f32_e32 v40, 0x3377d1cf, v38
	v_fma_f32 v38, v38, s53, v40
	s_nop 1
	v_add_f32_e32 v40, v39, v38
	v_cndmask_b32_e64 v63, 0, -v40, s[22:23]
	v_add_f32_e32 v38, v63, v28
	v_sub_f32_e32 v28, v41, v40
	v_cndmask_b32_e64 v64, v149, v28, s[22:23]
	v_mul_f32_e64 v28, |v34|, s49
	v_exp_f32_e32 v28, v28
	ds_bpermute_b32 v39, v46, v38
	ds_bpermute_b32 v52, v47, v38
	ds_bpermute_b32 v53, v48, v38
	v_add_f32_e32 v28, 1.0, v28
	s_waitcnt lgkmcnt(2)
	v_cndmask_b32_e64 v40, 0, v39, s[6:7]
	v_cmp_gt_u32_e64 s[22:23], s3, v106
	v_log_f32_e32 v28, v28
	s_waitcnt lgkmcnt(0)
; __device__ __forceinline__ void attn_phase(Frame& F, bf16* OZ) {
;     ...
;                 for (int sb = 0; sb < 4; ++sb) { tsum[sb] = 0.f;
; #pragma unroll
;                     for (int e = 0; e < 4; ++e) { const int s = 16 * sb + 4 * g4 + e; const float z = sc[sb][e]; const bool vis = (s < nvalid) && (spos0 + s < tpos);
;                         const float sp = fmaxf(z, 0.f) + __logf(1.0f + __expf(-fabsf(z)));
;                         lk[sb][e] = vis ? -sp : 0.f; sc[sb][e] = vis ? z - sp : -1e30f; tsum[sb] += lk[sb][e]; }
;                     const float v1 = __shfl_xor(tsum[sb], 16), v2 = __shfl_xor(tsum[sb], 32), v3 = __shfl_xor(tsum[sb], 48);
;                     above[sb] = ((g4 ^ 1) > g4 ? v1 : 0.f) + ((g4 ^ 2) > g4 ? v2 : 0.f) + ((g4 ^ 3) > g4 ? v3 : 0.f);
;                     ttot[sb] = (tsum[sb] + v1) + (v2 + v3); }
;                 float after = carry;
; #pragma unroll
;     ...
; #pragma unroll
;                     for (int e = 3; e >= 0; --e) { const float w = __expf(sc[sb][e] + run); run += lk[sb][e]; sc[sb][e] = w; }
;                     after += ttot[sb]; }
	v_pk_add_f32 v[38:39], v[38:39], v[52:53]
	v_cndmask_b32_e64 v54, 0, v52, s[4:5]
	v_pk_add_f32 v[38:39], v[38:39], v[38:39] op_sel_hi:[0,1]
	v_mul_f32_e32 v41, 0x3f317217, v28
	v_fma_f32 v41, v28, s53, -v41
	v_fmac_f32_e32 v41, 0x3377d1cf, v28
	v_or_b32_e32 v38, s2, v106
	v_fma_f32 v28, v28, s53, v41
	v_cmp_lt_i32_e64 s[26:27], v38, v90
	v_max_f32_e32 v38, v34, v34
	v_max_f32_e32 v38, 0, v38
	v_add_f32_e32 v28, v38, v28
	v_sub_f32_e32 v34, v34, v28
	s_and_b64 s[22:23], s[22:23], s[26:27]
	v_cndmask_b32_e64 v52, v149, v34, s[22:23]
	v_mul_f32_e64 v34, |v35|, s49
	v_exp_f32_e32 v34, v34
	v_or_b32_e32 v38, s2, v107
	v_sub_f32_e32 v28, 0, v28
	v_cmp_lt_i32_e64 s[26:27], v38, v90
	v_add_f32_e32 v34, 1.0, v34
	v_max_f32_e32 v38, v35, v35
	v_cndmask_b32_e64 v28, 0, v28, s[22:23]
	v_log_f32_e32 v34, v34
	v_cmp_gt_u32_e64 s[22:23], s3, v107
	v_max_f32_e32 v38, 0, v38
	s_and_b64 s[22:23], s[22:23], s[26:27]
	v_mul_f32_e32 v41, 0x3f317217, v34
	v_fma_f32 v41, v34, s53, -v41
	v_fmac_f32_e32 v41, 0x3377d1cf, v34
	v_fma_f32 v34, v34, s53, v41
	v_cndmask_b32_e64 v56, 0, v53, s[8:9]
	s_nop 0
	v_add_f32_e32 v34, v38, v34
	v_cndmask_b32_e64 v53, 0, -v34, s[22:23]
	v_sub_f32_e32 v34, v35, v34
	v_cndmask_b32_e64 v38, v149, v34, s[22:23]
	v_mul_f32_e64 v34, |v36|, s49
	v_exp_f32_e32 v34, v34
	v_or_b32_e32 v35, s2, v108
	v_cmp_lt_i32_e64 s[26:27], v35, v90
	v_max_f32_e32 v35, v36, v36
	v_add_f32_e32 v34, 1.0, v34
	v_cmp_gt_u32_e64 s[22:23], s3, v108
	v_max_f32_e32 v35, 0, v35
	v_log_f32_e32 v34, v34
	s_and_b64 s[22:23], s[22:23], s[26:27]
	v_add_f32_e32 v28, v53, v28
	v_mul_f32_e32 v41, 0x3f317217, v34
	v_fma_f32 v41, v34, s53, -v41
	v_fmac_f32_e32 v41, 0x3377d1cf, v34
	v_fma_f32 v34, v34, s53, v41
	s_nop 1
	v_add_f32_e32 v34, v35, v34
	v_cndmask_b32_e64 v41, 0, -v34, s[22:23]
	v_sub_f32_e32 v34, v36, v34
	v_cndmask_b32_e64 v55, v149, v34, s[22:23]
	v_mul_f32_e64 v34, |v37|, s49
	v_exp_f32_e32 v34, v34
	v_or_b32_e32 v35, s2, v109
	v_cmp_lt_i32_e64 s[26:27], v35, v90
	v_max_f32_e32 v35, v37, v37
	v_add_f32_e32 v34, 1.0, v34
	v_cmp_gt_u32_e64 s[22:23], s3, v109
	v_max_f32_e32 v35, 0, v35
	v_log_f32_e32 v34, v34
	s_and_b64 s[22:23], s[22:23], s[26:27]
	v_add_f32_e32 v28, v41, v28
	v_mul_f32_e32 v36, 0x3f317217, v34
	v_fma_f32 v36, v34, s53, -v36
	v_fmac_f32_e32 v36, 0x3377d1cf, v34
	v_fma_f32 v34, v34, s53, v36
	s_nop 1
	v_add_f32_e32 v57, v35, v34
	v_cndmask_b32_e64 v65, 0, -v57, s[22:23]
	v_add_f32_e32 v34, v65, v28
	ds_bpermute_b32 v35, v46, v34
	ds_bpermute_b32 v36, v47, v34
	v_sub_f32_e32 v28, v37, v57
	ds_bpermute_b32 v37, v48, v34
	v_cndmask_b32_e64 v28, v149, v28, s[22:23]
	s_waitcnt lgkmcnt(2)
	v_cndmask_b32_e64 v57, 0, v35, s[6:7]
	s_waitcnt lgkmcnt(1)
	v_cndmask_b32_e64 v68, 0, v36, s[4:5]
	v_add_f32_e32 v57, v68, v57
	s_waitcnt lgkmcnt(0)
	v_cndmask_b32_e64 v68, 0, v37, s[8:9]
	v_add_f32_e32 v57, v57, v68
	v_pk_add_f32 v[34:35], v[34:35], v[36:37]
	v_add_f32_e32 v36, 0, v57
	v_add_f32_e32 v28, v28, v36
	v_mul_f32_e32 v28, 0x3fb8aa3b, v28
	v_exp_f32_e32 v73, v28
	v_add_f32_e32 v28, v65, v36
	v_add_f32_e32 v36, v55, v28
	v_mul_f32_e32 v36, 0x3fb8aa3b, v36
	v_exp_f32_e32 v92, v36
	v_pk_add_f32 v[36:37], v[42:43], v[44:45]
	v_cmp_lt_i32_e64 s[22:23], v31, v90
	v_cndmask_b32_e64 v43, 0, -v51, s[18:19]
	v_cndmask_b32_e32 v42, 0, v50, vcc
	s_and_b64 vcc, s[0:1], s[20:21]
	v_pk_add_f32 v[44:45], v[42:43], v[4:5]
	v_cndmask_b32_e64 v51, 0, -v37, vcc
	v_cndmask_b32_e64 v50, 0, -v36, s[22:23]
	v_pk_add_f32 v[44:45], v[50:51], v[44:45]
	ds_bpermute_b32 v31, v47, v45
	v_add_f32_e32 v65, v41, v28
	v_add_f32_e32 v28, v38, v65
	v_mul_f32_e32 v28, 0x3fb8aa3b, v28
	v_mov_b32_e32 v55, v34
	v_mov_b32_e32 v41, v35
	v_exp_f32_e32 v72, v28
	v_sub_f32_e32 v28, v32, v36
	v_pk_add_f32 v[34:35], v[54:55], v[40:41]
	v_mov_b32_e32 v57, v2
	s_waitcnt lgkmcnt(0)
	v_pk_add_f32 v[40:41], v[30:31], v[44:45]
	v_cndmask_b32_e64 v32, v149, v28, s[22:23]
	v_pk_add_f32 v[34:35], v[34:35], v[56:57]
	ds_bpermute_b32 v28, v47, v40
	ds_bpermute_b32 v38, v46, v40
	v_add_f32_e32 v5, v34, v35
	ds_bpermute_b32 v34, v48, v40
	v_sub_f32_e32 v29, v29, v37
	s_waitcnt lgkmcnt(2)
	v_cndmask_b32_e64 v36, 0, v28, s[4:5]
	s_waitcnt lgkmcnt(1)
	v_cndmask_b32_e64 v42, 0, v38, s[6:7]
	v_add_f32_e32 v36, v36, v42
	s_waitcnt lgkmcnt(0)
	v_cndmask_b32_e64 v42, 0, v34, s[8:9]
	v_add_f32_e32 v36, v36, v42
	ds_bpermute_b32 v42, v46, v45
	ds_bpermute_b32 v37, v48, v45
	v_cndmask_b32_e32 v44, v149, v29, vcc
	v_cndmask_b32_e64 v29, 0, v31, s[4:5]
	v_pk_add_f32 v[34:35], v[38:39], v[34:35]
	s_waitcnt lgkmcnt(1)
; __device__ __forceinline__ unsigned pk2(float lo, float hi) { const cvt_f2 v = {lo, hi}; const cvt_b2 r = __builtin_convertvector(v, cvt_b2); return __builtin_bit_cast(unsigned, r); }
; #define MFMA16(a, b, c) __builtin_amdgcn_mfma_f32_16x16x32_bf16((a), (b), (c), 0, 0, 0)
; __device__ __forceinline__ void attn_phase(Frame& F, bf16* OZ) {
;     ...
;                 float after = carry;
; #pragma unroll
;     ...
; #pragma unroll
;                     for (int e = 3; e >= 0; --e) { const float w = __expf(sc[sb][e] + run); run += lk[sb][e]; sc[sb][e] = w; }
;                     after += ttot[sb]; }
;                 carry = after;
; #pragma unroll
;                 for (int kk = 0; kk < 2; ++kk) { v4u pkd; pkd.x = pk2(sc[2 * kk][0], sc[2 * kk][1]); pkd.y = pk2(sc[2 * kk][2], sc[2 * kk][3]); pkd.z = pk2(sc[2 * kk + 1][0], sc[2 * kk + 1][1]); pkd.w = pk2(sc[2 * kk + 1][2], sc[2 * kk + 1][3]);
;                     const bf16x8 pf = __builtin_bit_cast(bf16x8, pkd);
; #pragma unroll
;                     for (int dh = 0; dh < 2; ++dh) { unsigned aa[4]; bf16x8 vf[4];
; #pragma unroll
;                         for (int i = 0; i < 4; ++i) aa[i] = F.lds0 + VS + (32 * kk + 4 * g4 + q) * ST_ + (32 * (2 * dh + (i >> 1)) + 8 * p + 4 * (i & 1)) * 2;
;                         tr_read_x4(aa, 16 * ST_, vf);
; #pragma unroll
;                         for (int i = 0; i < 4; ++i) oacc[4 * dh + i] = MFMA16(vf[i], pf, oacc[4 * dh + i]); } }
;                 done = __all(carry < ATT_THR);
	v_cndmask_b32_e64 v31, 0, v42, s[6:7]
	v_add_f32_e32 v29, v29, v31
	s_waitcnt lgkmcnt(0)
	v_cndmask_b32_e64 v31, 0, v37, s[8:9]
	v_add_f32_e32 v31, v29, v31
	v_add_f32_e32 v31, v31, v35
	v_add_f32_e32 v29, v42, v37
	v_add_f32_e32 v37, v44, v31
	v_add_f32_e32 v31, v51, v31
	v_add_f32_e32 v38, v59, v31
	v_add_f32_e32 v31, v43, v31
	v_add_f32_e32 v27, v27, v31
	v_pk_add_f32 v[28:29], v[40:41], v[28:29]
	v_mul_f32_e32 v27, 0x3fb8aa3b, v27
	v_exp_f32_e32 v39, v27
	v_add_f32_e32 v27, v58, v31
	v_pk_add_f32 v[96:97], v[28:29], v[34:35]
	v_add_f32_e32 v26, v26, v27
	v_add_f32_e32 v27, v36, v97
	v_add_f32_e32 v28, v33, v27
	v_add_f32_e32 v27, v30, v27
	v_add_f32_e32 v29, v32, v27
	v_add_f32_e32 v27, v50, v27
	v_mul_f32_e32 v28, 0x3fb8aa3b, v28
	v_mul_f32_e32 v29, 0x3fb8aa3b, v29
	v_add_f32_e32 v4, v4, v27
	v_exp_f32_e32 v28, v28
	v_add_f32_e32 v3, v3, v4
	v_exp_f32_e32 v4, v29
	v_add_f32_e32 v30, v49, v27
	v_mul_f32_e32 v37, 0x3fb8aa3b, v37
	v_mul_f32_e32 v38, 0x3fb8aa3b, v38
	v_mul_f32_e32 v26, 0x3fb8aa3b, v26
	v_mul_f32_e32 v30, 0x3fb8aa3b, v30
	v_mul_f32_e32 v3, 0x3fb8aa3b, v3
	v_exp_f32_e32 v37, v37
	v_exp_f32_e32 v30, v30
	v_exp_f32_e32 v3, v3
	v_exp_f32_e32 v29, v26
	v_exp_f32_e32 v31, v38
	v_cvt_pk_bf16_f32 v27, v4, v28
	v_add_f32_e32 v4, v64, v5
	v_add_f32_e32 v5, v63, v5
	v_add_f32_e32 v46, v61, v5
	v_add_f32_e32 v5, v60, v5
	v_add_f32_e32 v47, v53, v65
	v_add_f32_e32 v62, v62, v5
	v_add_f32_e32 v5, v67, v5
	v_cvt_pk_bf16_f32 v26, v3, v30
	v_cvt_pk_bf16_f32 v28, v29, v39
	v_cvt_pk_bf16_f32 v29, v31, v37
	ds_read_b64_tr_b16 v[42:43], v110
	ds_read_b64_tr_b16 v[44:45], v114
	ds_read_b64_tr_b16 v[38:39], v111
	ds_read_b64_tr_b16 v[40:41], v115
	ds_read_b64_tr_b16 v[34:35], v112
	ds_read_b64_tr_b16 v[36:37], v116
	ds_read_b64_tr_b16 v[30:31], v113
	ds_read_b64_tr_b16 v[32:33], v117
	s_waitcnt lgkmcnt(0)
	v_add_f32_e32 v3, v52, v47
	v_add_f32_e32 v5, v66, v5
	v_mul_f32_e32 v3, 0x3fb8aa3b, v3
	v_mul_f32_e32 v4, 0x3fb8aa3b, v4
	v_mul_f32_e32 v70, 0x3fb8aa3b, v46
	ds_read_b64_tr_b16 v[58:59], v118
	ds_read_b64_tr_b16 v[60:61], v122
	ds_read_b64_tr_b16 v[54:55], v119
	ds_read_b64_tr_b16 v[56:57], v123
	ds_read_b64_tr_b16 v[50:51], v120
	ds_read_b64_tr_b16 v[52:53], v124
	ds_read_b64_tr_b16 v[46:47], v121
	ds_read_b64_tr_b16 v[48:49], v125
	s_waitcnt lgkmcnt(0)
	v_mul_f32_e32 v62, 0x3fb8aa3b, v62
	v_mul_f32_e32 v5, 0x3fb8aa3b, v5
	v_exp_f32_e32 v4, v4
	v_exp_f32_e32 v71, v62
	v_mfma_f32_16x16x32_bf16 v[66:69], v[50:53], v[26:29], 0
	v_exp_f32_e32 v5, v5
	v_exp_f32_e32 v50, v70
	v_exp_f32_e32 v3, v3
	v_mfma_f32_16x16x32_bf16 v[42:45], v[42:45], v[26:29], 0
	v_cvt_pk_bf16_f32 v70, v5, v71
	v_cvt_pk_bf16_f32 v71, v50, v4
	v_cvt_pk_bf16_f32 v72, v3, v72
	v_mfma_f32_16x16x32_bf16 v[38:41], v[38:41], v[26:29], 0
	v_cvt_pk_bf16_f32 v73, v92, v73
	v_mfma_f32_16x16x32_bf16 v[34:37], v[34:37], v[26:29], 0
	v_mfma_f32_16x16x32_bf16 v[30:33], v[30:33], v[26:29], 0
	v_mfma_f32_16x16x32_bf16 v[58:61], v[58:61], v[26:29], 0
	v_mfma_f32_16x16x32_bf16 v[62:65], v[54:57], v[26:29], 0
	v_mfma_f32_16x16x32_bf16 v[26:29], v[46:49], v[26:29], 0
	ds_read_b64_tr_b16 v[54:55], v126
	ds_read_b64_tr_b16 v[56:57], v130
	ds_read_b64_tr_b16 v[50:51], v127
	ds_read_b64_tr_b16 v[52:53], v131
	ds_read_b64_tr_b16 v[46:47], v128
	ds_read_b64_tr_b16 v[48:49], v132
	ds_read_b64_tr_b16 v[92:93], v129
	ds_read_b64_tr_b16 v[94:95], v133
	s_waitcnt lgkmcnt(0)
	s_nop 0
	v_mfma_f32_16x16x32_bf16 v[54:57], v[54:57], v[70:73], v[42:45]
	v_mfma_f32_16x16x32_bf16 v[50:53], v[50:53], v[70:73], v[38:41]
	v_mfma_f32_16x16x32_bf16 v[46:49], v[46:49], v[70:73], v[34:37]
	v_mfma_f32_16x16x32_bf16 v[42:45], v[92:95], v[70:73], v[30:33]
	ds_read_b64_tr_b16 v[38:39], v134
	ds_read_b64_tr_b16 v[40:41], v138
	ds_read_b64_tr_b16 v[34:35], v135
	ds_read_b64_tr_b16 v[36:37], v139
	ds_read_b64_tr_b16 v[30:31], v136
	ds_read_b64_tr_b16 v[32:33], v140
	ds_read_b64_tr_b16 v[92:93], v137
	ds_read_b64_tr_b16 v[94:95], v141
	s_waitcnt lgkmcnt(0)
	s_nop 0
	v_mfma_f32_16x16x32_bf16 v[38:41], v[38:41], v[70:73], v[58:61]
	v_mfma_f32_16x16x32_bf16 v[34:37], v[34:37], v[70:73], v[62:65]
	v_mfma_f32_16x16x32_bf16 v[30:33], v[30:33], v[70:73], v[66:69]
	v_mfma_f32_16x16x32_bf16 v[26:29], v[92:95], v[70:73], v[26:29]
	v_add_f32_e32 v93, v96, v97
	v_cmp_gt_f32_e32 vcc, s55, v93
	s_cmp_eq_u64 vcc, exec
	s_cselect_b64 s[0:1], -1, 0
	s_and_saveexec_b64 s[2:3], s[10:11]
	s_cbranch_execnz .LBB0_1900
	s_branch .LBB0_1901

; __device__ __forceinline__ float silu_f(float v) { return v * __builtin_amdgcn_rcpf(1.0f + __builtin_amdgcn_exp2f(-1.44269504f * v)); }
; __device__ __forceinline__ unsigned pk2(float lo, float hi) { const cvt_f2 v = {lo, hi}; const cvt_b2 r = __builtin_convertvector(v, cvt_b2); return __builtin_bit_cast(unsigned, r); }
; __device__ __forceinline__ float silu_f(float v) { return v * __builtin_amdgcn_rcpf(1.0f + __builtin_amdgcn_exp2f(-1.44269504f * v)); }
; __device__ __forceinline__ void attn_phase(Frame& F, bf16* OZ) {
;     ...
;         if (active) {
;             const size_t rb = (size_t)(qrow0 + tq) * D + h * 128 + 8 * g4;
; #pragma unroll
;             for (int dp = 0; dp < 4; ++dp) { const v4u zz = *(const v4u*)(CZ + (((size_t)((qrow0 >> 4) + wave) * 64 + (h >> 1) * 8 + 2 * dp + (h & 1)) * 64 + lane) * 8);
;                 const f32x4 o = oacc[2 * dp], o2 = oacc[2 * dp + 1]; v4u w;
;                 w.x = pk2(o.x * silu_f(bflo(zz.x)), o.y * silu_f(bfhi(zz.x))); w.y = pk2(o.z * silu_f(bflo(zz.y)), o.w * silu_f(bfhi(zz.y)));
;                 w.z = pk2(o2.x * silu_f(bflo(zz.z)), o2.y * silu_f(bfhi(zz.z))); w.w = pk2(o2.z * silu_f(bflo(zz.w)), o2.w * silu_f(bfhi(zz.w))); *(v4u*)(OZ + ((size_t)((qrow0 >> 4) + wave) * 64 + h * 4 + dp) * 512 + (((l15 * 64 + g4 * 16) ^ ((l15 >> 3) << 5)) >> 1)) = w; }
.LBB0_1902:
	s_andn2_b64 vcc, exec, s[40:41]
	s_cbranch_vccnz .LBB0_1880
	s_ashr_i32 s0, s59, 4
	s_add_i32 s0, s0, s96
	s_lshl_b32 s18, s58, 2
	s_ashr_i32 s1, s0, 31
	s_and_b32 s2, s18, 56
	s_and_b32 s3, s57, 1
	s_lshl_b64 s[0:1], s[0:1], 6
	s_or_b32 s2, s2, s3
	s_or_b32 s2, s2, s0
	s_mov_b32 s3, s1
	s_lshl_b64 s[14:15], s[2:3], 10
	v_lshl_add_u64 v[4:5], v[78:79], 0, s[14:15]
	global_load_dwordx4 v[10:13], v[4:5], off
	global_load_dwordx4 v[192:195], v[4:5], off offset:2048
	v_add_co_u32_e32 v204, vcc, 0x1000, v4
	s_nop 1
	v_addc_co_u32_e32 v205, vcc, 0, v5, vcc
	global_load_dwordx4 v[196:199], v[204:205], off
	global_load_dwordx4 v[200:203], v[204:205], off offset:2048
	s_or_b32 s0, s18, s0
	s_mov_b32 s15, s1
	s_lshl_b64 s[18:19], s[0:1], 10
	s_or_b32 s14, s2, 2
	v_lshl_add_u64 v[4:5], v[80:81], 0, s[18:19]
	s_lshl_b64 s[14:15], s[14:15], 10
	v_lshl_add_u64 v[14:15], v[78:79], 0, s[14:15]
	s_mov_b32 s15, s1
	s_or_b32 s14, s0, 1
	s_mov_b32 s19, s1
	s_or_b32 s18, s2, 4
	s_lshl_b64 s[14:15], s[14:15], 10
	s_lshl_b64 s[18:19], s[18:19], 10
	s_or_b32 s2, s2, 6
	s_lshl_b64 s[2:3], s[2:3], 10
	s_waitcnt vmcnt(3)
	v_lshlrev_b32_e32 v16, 16, v10
	v_and_b32_e32 v17, 0xffff0000, v10
	v_lshlrev_b32_e32 v10, 16, v11
	v_and_b32_e32 v11, 0xffff0000, v11
	v_lshlrev_b32_e32 v18, 16, v12
	v_and_b32_e32 v19, 0xffff0000, v12
	v_lshlrev_b32_e32 v12, 16, v13
	v_and_b32_e32 v13, 0xffff0000, v13
	v_mul_f32_e32 v3, 0xbfb8aa3b, v16
	v_mul_f32_e32 v20, 0xbfb8aa3b, v17
	v_mul_f32_e32 v21, 0xbfb8aa3b, v10
	v_mul_f32_e32 v22, 0xbfb8aa3b, v11
	v_mul_f32_e32 v23, 0xbfb8aa3b, v18
	v_mul_f32_e32 v24, 0xbfb8aa3b, v19
	v_mul_f32_e32 v25, 0xbfb8aa3b, v12
	v_mul_f32_e32 v58, 0xbfb8aa3b, v13
	v_exp_f32_e32 v3, v3
	v_exp_f32_e32 v20, v20
	v_exp_f32_e32 v21, v21
	v_exp_f32_e32 v22, v22
	v_exp_f32_e32 v23, v23
	v_exp_f32_e32 v24, v24
	v_exp_f32_e32 v25, v25
	v_exp_f32_e32 v58, v58
	v_add_f32_e32 v3, 1.0, v3
	v_add_f32_e32 v59, 1.0, v20
	v_add_f32_e32 v60, 1.0, v21
	v_add_f32_e32 v61, 1.0, v22
	v_add_f32_e32 v62, 1.0, v23
	v_add_f32_e32 v63, 1.0, v24
	v_add_f32_e32 v64, 1.0, v25
	v_add_f32_e32 v65, 1.0, v58
	v_rcp_f32_e32 v20, v3
	v_rcp_f32_e32 v21, v59
	v_rcp_f32_e32 v22, v60
	v_rcp_f32_e32 v23, v61
	v_rcp_f32_e32 v24, v62
	v_rcp_f32_e32 v25, v63
	v_rcp_f32_e32 v58, v64
	v_rcp_f32_e32 v59, v65
	v_pk_mul_f32 v[16:17], v[20:21], v[16:17]
	v_pk_mul_f32 v[10:11], v[22:23], v[10:11]
	v_pk_mul_f32 v[18:19], v[24:25], v[18:19]
	v_pk_mul_f32 v[12:13], v[58:59], v[12:13]
	v_pk_mul_f32 v[16:17], v[54:55], v[16:17]
	v_pk_mul_f32 v[20:21], v[56:57], v[10:11]
	v_pk_mul_f32 v[18:19], v[50:51], v[18:19]
	v_pk_mul_f32 v[22:23], v[52:53], v[12:13]
	v_cvt_pk_bf16_f32 v10, v16, v17
	v_cvt_pk_bf16_f32 v11, v20, v21
	v_cvt_pk_bf16_f32 v12, v18, v19
	v_cvt_pk_bf16_f32 v13, v22, v23
	global_store_dwordx4 v[4:5], v[10:13], off
	v_lshl_add_u64 v[4:5], v[80:81], 0, s[14:15]
	v_lshl_add_u64 v[14:15], v[78:79], 0, s[18:19]
	s_mov_b32 s15, s1
	s_or_b32 s14, s0, 2
	s_lshl_b64 s[14:15], s[14:15], 10
	s_or_b32 s0, s0, 3
	s_lshl_b64 s[0:1], s[0:1], 10
	s_waitcnt vmcnt(3)
	v_lshlrev_b32_e32 v16, 16, v192
	v_and_b32_e32 v17, 0xffff0000, v192
	v_lshlrev_b32_e32 v10, 16, v193
	v_and_b32_e32 v11, 0xffff0000, v193
	v_lshlrev_b32_e32 v18, 16, v194
	v_and_b32_e32 v19, 0xffff0000, v194
	v_lshlrev_b32_e32 v12, 16, v195
	v_and_b32_e32 v13, 0xffff0000, v195
	v_mul_f32_e32 v3, 0xbfb8aa3b, v16
	v_mul_f32_e32 v20, 0xbfb8aa3b, v17
	v_mul_f32_e32 v21, 0xbfb8aa3b, v10
	v_mul_f32_e32 v22, 0xbfb8aa3b, v11
	v_mul_f32_e32 v23, 0xbfb8aa3b, v18
	v_mul_f32_e32 v24, 0xbfb8aa3b, v19
	v_mul_f32_e32 v25, 0xbfb8aa3b, v12
	v_mul_f32_e32 v50, 0xbfb8aa3b, v13
	v_exp_f32_e32 v3, v3
	v_exp_f32_e32 v20, v20
	v_exp_f32_e32 v21, v21
	v_exp_f32_e32 v22, v22
	v_exp_f32_e32 v23, v23
	v_exp_f32_e32 v24, v24
	v_exp_f32_e32 v25, v25
	v_exp_f32_e32 v50, v50
	v_add_f32_e32 v3, 1.0, v3
	v_add_f32_e32 v51, 1.0, v20
	v_add_f32_e32 v52, 1.0, v21
	v_add_f32_e32 v53, 1.0, v22
	v_add_f32_e32 v54, 1.0, v23
	v_add_f32_e32 v55, 1.0, v24
	v_add_f32_e32 v56, 1.0, v25
	v_add_f32_e32 v57, 1.0, v50
	v_rcp_f32_e32 v20, v3
	v_rcp_f32_e32 v21, v51
	v_rcp_f32_e32 v22, v52
	v_rcp_f32_e32 v23, v53
	v_rcp_f32_e32 v24, v54
	v_rcp_f32_e32 v25, v55
	v_rcp_f32_e32 v50, v56
	v_rcp_f32_e32 v51, v57
	v_pk_mul_f32 v[16:17], v[20:21], v[16:17]
	v_pk_mul_f32 v[10:11], v[22:23], v[10:11]
	v_pk_mul_f32 v[18:19], v[24:25], v[18:19]
	v_pk_mul_f32 v[12:13], v[50:51], v[12:13]
	v_pk_mul_f32 v[16:17], v[46:47], v[16:17]
	v_pk_mul_f32 v[20:21], v[48:49], v[10:11]
	v_pk_mul_f32 v[18:19], v[42:43], v[18:19]
	v_pk_mul_f32 v[22:23], v[44:45], v[12:13]
	v_cvt_pk_bf16_f32 v10, v16, v17
	v_cvt_pk_bf16_f32 v11, v20, v21
	v_cvt_pk_bf16_f32 v12, v18, v19
	v_cvt_pk_bf16_f32 v13, v22, v23
	global_store_dwordx4 v[4:5], v[10:13], off
	v_lshl_add_u64 v[4:5], v[80:81], 0, s[14:15]
	v_lshl_add_u64 v[14:15], v[78:79], 0, s[2:3]
	s_waitcnt vmcnt(3)
; __device__ __forceinline__ float silu_f(float v) { return v * __builtin_amdgcn_rcpf(1.0f + __builtin_amdgcn_exp2f(-1.44269504f * v)); }
; __device__ __forceinline__ unsigned pk2(float lo, float hi) { const cvt_f2 v = {lo, hi}; const cvt_b2 r = __builtin_convertvector(v, cvt_b2); return __builtin_bit_cast(unsigned, r); }
; __device__ __forceinline__ float silu_f(float v) { return v * __builtin_amdgcn_rcpf(1.0f + __builtin_amdgcn_exp2f(-1.44269504f * v)); }
; __device__ __forceinline__ void attn_phase(Frame& F, bf16* OZ) {
;     ...
;             for (int dp = 0; dp < 4; ++dp) { const v4u zz = *(const v4u*)(CZ + (((size_t)((qrow0 >> 4) + wave) * 64 + (h >> 1) * 8 + 2 * dp + (h & 1)) * 64 + lane) * 8);
;                 const f32x4 o = oacc[2 * dp], o2 = oacc[2 * dp + 1]; v4u w;
;                 w.x = pk2(o.x * silu_f(bflo(zz.x)), o.y * silu_f(bfhi(zz.x))); w.y = pk2(o.z * silu_f(bflo(zz.y)), o.w * silu_f(bfhi(zz.y)));
;                 w.z = pk2(o2.x * silu_f(bflo(zz.z)), o2.y * silu_f(bfhi(zz.z))); w.w = pk2(o2.z * silu_f(bflo(zz.w)), o2.w * silu_f(bfhi(zz.w))); *(v4u*)(OZ + ((size_t)((qrow0 >> 4) + wave) * 64 + h * 4 + dp) * 512 + (((l15 * 64 + g4 * 16) ^ ((l15 >> 3) << 5)) >> 1)) = w; }
;         }
;         __syncthreads();
	v_lshlrev_b32_e32 v16, 16, v196
	v_and_b32_e32 v17, 0xffff0000, v196
	v_lshlrev_b32_e32 v10, 16, v197
	v_and_b32_e32 v11, 0xffff0000, v197
	v_lshlrev_b32_e32 v18, 16, v198
	v_and_b32_e32 v19, 0xffff0000, v198
	v_lshlrev_b32_e32 v12, 16, v199
	v_and_b32_e32 v13, 0xffff0000, v199
	v_mul_f32_e32 v3, 0xbfb8aa3b, v16
	v_mul_f32_e32 v20, 0xbfb8aa3b, v17
	v_mul_f32_e32 v21, 0xbfb8aa3b, v10
	v_mul_f32_e32 v22, 0xbfb8aa3b, v11
	v_mul_f32_e32 v23, 0xbfb8aa3b, v18
	v_mul_f32_e32 v24, 0xbfb8aa3b, v19
	v_mul_f32_e32 v25, 0xbfb8aa3b, v12
	v_mul_f32_e32 v42, 0xbfb8aa3b, v13
	v_exp_f32_e32 v3, v3
	v_exp_f32_e32 v20, v20
	v_exp_f32_e32 v21, v21
	v_exp_f32_e32 v22, v22
	v_exp_f32_e32 v23, v23
	v_exp_f32_e32 v24, v24
	v_exp_f32_e32 v25, v25
	v_exp_f32_e32 v42, v42
	v_add_f32_e32 v3, 1.0, v3
	v_add_f32_e32 v43, 1.0, v20
	v_add_f32_e32 v44, 1.0, v21
	v_add_f32_e32 v45, 1.0, v22
	v_add_f32_e32 v46, 1.0, v23
	v_add_f32_e32 v47, 1.0, v24
	v_add_f32_e32 v48, 1.0, v25
	v_add_f32_e32 v49, 1.0, v42
	v_rcp_f32_e32 v20, v3
	v_rcp_f32_e32 v21, v43
	v_rcp_f32_e32 v22, v44
	v_rcp_f32_e32 v23, v45
	v_rcp_f32_e32 v24, v46
	v_rcp_f32_e32 v25, v47
	v_rcp_f32_e32 v42, v48
	v_rcp_f32_e32 v43, v49
	v_pk_mul_f32 v[16:17], v[20:21], v[16:17]
	v_pk_mul_f32 v[10:11], v[22:23], v[10:11]
	v_pk_mul_f32 v[18:19], v[24:25], v[18:19]
	v_pk_mul_f32 v[12:13], v[42:43], v[12:13]
	v_pk_mul_f32 v[16:17], v[38:39], v[16:17]
	v_pk_mul_f32 v[20:21], v[40:41], v[10:11]
	v_pk_mul_f32 v[18:19], v[34:35], v[18:19]
	v_pk_mul_f32 v[22:23], v[36:37], v[12:13]
	v_cvt_pk_bf16_f32 v10, v16, v17
	v_cvt_pk_bf16_f32 v11, v20, v21
	v_cvt_pk_bf16_f32 v12, v18, v19
	v_cvt_pk_bf16_f32 v13, v22, v23
	global_store_dwordx4 v[4:5], v[10:13], off
	s_waitcnt vmcnt(3)
	v_lshlrev_b32_e32 v4, 16, v200
	v_and_b32_e32 v5, 0xffff0000, v200
	v_lshlrev_b32_e32 v10, 16, v201
	v_and_b32_e32 v11, 0xffff0000, v201
	v_lshlrev_b32_e32 v14, 16, v202
	v_and_b32_e32 v15, 0xffff0000, v202
	v_lshlrev_b32_e32 v12, 16, v203
	v_and_b32_e32 v13, 0xffff0000, v203
	v_mul_f32_e32 v3, 0xbfb8aa3b, v4
	v_mul_f32_e32 v16, 0xbfb8aa3b, v5
	v_mul_f32_e32 v17, 0xbfb8aa3b, v10
	v_mul_f32_e32 v18, 0xbfb8aa3b, v11
	v_mul_f32_e32 v19, 0xbfb8aa3b, v14
	v_mul_f32_e32 v20, 0xbfb8aa3b, v15
	v_mul_f32_e32 v21, 0xbfb8aa3b, v12
	v_mul_f32_e32 v22, 0xbfb8aa3b, v13
	v_exp_f32_e32 v3, v3
	v_exp_f32_e32 v16, v16
	v_exp_f32_e32 v17, v17
	v_exp_f32_e32 v18, v18
	v_exp_f32_e32 v19, v19
	v_exp_f32_e32 v20, v20
	v_exp_f32_e32 v21, v21
	v_exp_f32_e32 v22, v22
	v_add_f32_e32 v3, 1.0, v3
	v_add_f32_e32 v23, 1.0, v16
	v_add_f32_e32 v24, 1.0, v17
	v_add_f32_e32 v25, 1.0, v18
	v_add_f32_e32 v34, 1.0, v19
	v_add_f32_e32 v35, 1.0, v20
	v_add_f32_e32 v36, 1.0, v21
	v_add_f32_e32 v37, 1.0, v22
	v_rcp_f32_e32 v16, v3
	v_rcp_f32_e32 v17, v23
	v_rcp_f32_e32 v18, v24
	v_rcp_f32_e32 v19, v25
	v_rcp_f32_e32 v20, v34
	v_rcp_f32_e32 v21, v35
	v_rcp_f32_e32 v22, v36
	v_rcp_f32_e32 v23, v37
	v_pk_mul_f32 v[4:5], v[16:17], v[4:5]
	v_pk_mul_f32 v[10:11], v[18:19], v[10:11]
	v_pk_mul_f32 v[14:15], v[20:21], v[14:15]
	v_pk_mul_f32 v[12:13], v[22:23], v[12:13]
	v_pk_mul_f32 v[4:5], v[30:31], v[4:5]
	v_pk_mul_f32 v[16:17], v[32:33], v[10:11]
	v_pk_mul_f32 v[14:15], v[26:27], v[14:15]
	v_pk_mul_f32 v[18:19], v[28:29], v[12:13]
	v_cvt_pk_bf16_f32 v10, v4, v5
	v_cvt_pk_bf16_f32 v11, v16, v17
	v_cvt_pk_bf16_f32 v12, v14, v15
	v_cvt_pk_bf16_f32 v13, v18, v19
	v_lshl_add_u64 v[4:5], v[80:81], 0, s[0:1]
	global_store_dwordx4 v[4:5], v[10:13], off
	s_branch .LBB0_1880

; #define LAS __attribute__((address_space(3)))
; #define MFMA16(a, b, c) __builtin_amdgcn_mfma_f32_16x16x32_bf16((a), (b), (c), 0, 0, 0)
; __device__ __forceinline__ void attn_phase(Frame& F, bf16* OZ) {
;     ...
;             const int spos0 = !smp ? (2 * qb + 1 - kb) * 64 : (kb == 0 ? 1024 : 1024 - 64 * kb), nvalid = (smp && kb == 0) ? 16 : 64;
;             if (kb > 0) { ATT_LOAD_KV(kb); __syncthreads(); }
;             bool done = true;
;             const bool none_visible = spos0 > __builtin_amdgcn_readfirstlane(tpos - l15) + 14;
;             if (active && none_visible) done = false;
;             if (active && !none_visible) {
;                 f32x4 sc[4];
; #pragma unroll
;                 for (int sb = 0; sb < 4; ++sb) { sc[sb] = (f32x4){0.f, 0.f, 0.f, 0.f};
; #pragma unroll
;                     for (int ks = 0; ks < 4; ++ks) { const bf16x8 a = *(const LAS bf16x8*)(L + KS + (16 * sb + l15) * ST_ + (32 * ks + 8 * g4) * 2); sc[sb] = MFMA16(a, qf[ks], sc[sb]); } }
;                 float lk[4][4], tsum[4], above[4], ttot[4];
; #pragma unroll
;                 for (int sb = 0; sb < 4; ++sb) { tsum[sb] = 0.f;
; #pragma unroll
;                     for (int e = 0; e < 4; ++e) { const int s = 16 * sb + 4 * g4 + e; const float z = sc[sb][e]; const bool vis = (s < nvalid) && (spos0 + s < tpos);
;                         const float sp = fmaxf(z, 0.f) + __logf(1.0f + __expf(-fabsf(z)));
;                         lk[sb][e] = vis ? -sp : 0.f; sc[sb][e] = vis ? z - sp : -1e30f; tsum[sb] += lk[sb][e]; }
.LBB0_1910:
	s_add_i32 s1, s60, s21
	s_and_b64 s[18:19], s[38:39], exec
	s_cselect_b32 s18, s0, s1
	v_readfirstlane_b32 s0, v150
	s_add_i32 s0, s0, 14
	s_cmp_gt_i32 s18, s0
	s_cselect_b64 s[0:1], -1, 0
	s_andn2_b64 s[0:1], s[0:1], s[64:65]
	s_or_b64 s[24:25], s[42:43], s[0:1]
	s_or_b64 s[24:25], s[24:25], s[64:65]
	s_and_b64 vcc, exec, s[24:25]
	s_waitcnt vmcnt(3)
	ds_write_b128 v144, v[58:61] offset:34816
	s_waitcnt vmcnt(2)
	ds_write_b128 v144, v[62:65] offset:52224
	s_waitcnt vmcnt(1)
	ds_write_b128 v145, v[66:69] offset:34816
	s_waitcnt vmcnt(0)
	ds_write_b128 v145, v[70:73] offset:52224
	s_waitcnt lgkmcnt(0)
	s_barrier
	s_cbranch_vccnz .LBB0_1912
	ds_read_b128 v[58:61], v146 offset:34816
	ds_read_b128 v[62:65], v146 offset:34880
	ds_read_b128 v[66:69], v146 offset:39168
	ds_read_b128 v[70:73], v146 offset:39232
	ds_read_b128 v[94:97], v146 offset:34944
	v_and_b32_e32 v5, 64, v147
	s_waitcnt lgkmcnt(4)
	v_mfma_f32_16x16x32_bf16 v[58:61], v[58:61], v[10:13], 0
	v_xor_b32_e32 v4, 16, v147
	v_add_u32_e32 v5, 64, v5
	v_cmp_lt_i32_e32 vcc, v4, v5
	s_waitcnt lgkmcnt(3)
	v_mfma_f32_16x16x32_bf16 v[58:61], v[62:65], v[14:17], v[58:61]
	ds_read_b128 v[62:65], v146 offset:35008
	ds_read_b128 v[154:157], v146 offset:39296
	ds_read_b128 v[158:161], v146 offset:39360
	v_cndmask_b32_e32 v4, v147, v4, vcc
	s_waitcnt lgkmcnt(5)
	v_mfma_f32_16x16x32_bf16 v[66:69], v[66:69], v[10:13], 0
	s_waitcnt lgkmcnt(3)
	v_mfma_f32_16x16x32_bf16 v[58:61], v[94:97], v[18:21], v[58:61]
	ds_read_b128 v[94:97], v146 offset:43520
	ds_read_b128 v[162:165], v146 offset:43584
	ds_read_b128 v[166:169], v146 offset:43648
	ds_read_b128 v[170:173], v146 offset:43712
	ds_read_b128 v[174:177], v146 offset:47872
	ds_read_b128 v[178:181], v146 offset:47936
	ds_read_b128 v[184:187], v146 offset:48000
	ds_read_b128 v[188:191], v146 offset:48064
	s_waitcnt lgkmcnt(10)
	v_mfma_f32_16x16x32_bf16 v[62:65], v[62:65], v[22:25], v[58:61]
	v_mfma_f32_16x16x32_bf16 v[58:61], v[70:73], v[14:17], v[66:69]
	s_waitcnt lgkmcnt(9)
	v_mfma_f32_16x16x32_bf16 v[58:61], v[154:157], v[18:21], v[58:61]
	v_lshlrev_b32_e32 v156, 2, v4
	v_xor_b32_e32 v4, 32, v147
	v_cmp_lt_i32_e32 vcc, v4, v5
	s_waitcnt lgkmcnt(8)
	v_mfma_f32_16x16x32_bf16 v[58:61], v[158:161], v[22:25], v[58:61]
	v_or_b32_e32 v158, s18, v1
	v_cndmask_b32_e32 v4, v147, v4, vcc
	v_lshlrev_b32_e32 v154, 2, v4
	v_xor_b32_e32 v4, 48, v147
	v_cmp_lt_i32_e32 vcc, v4, v5
	s_waitcnt lgkmcnt(7)
	v_mfma_f32_16x16x32_bf16 v[66:69], v[94:97], v[10:13], 0
	v_or_b32_e32 v159, s18, v86
	v_cndmask_b32_e32 v4, v147, v4, vcc
	v_lshlrev_b32_e32 v155, 2, v4
	v_mul_f32_e64 v4, |v62|, s49
	v_exp_f32_e32 v4, v4
	s_waitcnt lgkmcnt(6)
	v_mfma_f32_16x16x32_bf16 v[66:69], v[162:165], v[14:17], v[66:69]
	v_or_b32_e32 v162, s18, v88
	v_add_f32_e32 v4, 1.0, v4
	s_waitcnt lgkmcnt(5)
	v_mfma_f32_16x16x32_bf16 v[66:69], v[166:169], v[18:21], v[66:69]
	v_log_f32_e32 v4, v4
	v_max_f32_e32 v5, v62, v62
	v_max_f32_e32 v5, 0, v5
	s_waitcnt lgkmcnt(4)
	v_mfma_f32_16x16x32_bf16 v[70:73], v[170:173], v[22:25], v[66:69]
	v_mul_f32_e32 v92, 0x3f317217, v4
	v_fma_f32 v92, v4, s53, -v92
	v_fmac_f32_e32 v92, 0x3377d1cf, v4
	v_fma_f32 v4, v4, s53, v92
	s_waitcnt lgkmcnt(3)
	v_mfma_f32_16x16x32_bf16 v[66:69], v[174:177], v[10:13], 0
	v_mul_f32_e64 v92, |v63|, s49
	v_exp_f32_e32 v92, v92
	v_add_f32_e32 v4, v5, v4
	v_sub_f32_e32 v161, v62, v4
	v_sub_f32_e32 v160, 0, v4
	v_add_f32_e32 v4, 1.0, v92
	v_max_f32_e32 v62, v63, v63
	v_max_f32_e32 v62, 0, v62
	v_log_f32_e32 v4, v4
	v_or_b32_e32 v5, s18, v98
	s_waitcnt lgkmcnt(2)
	v_mfma_f32_16x16x32_bf16 v[66:69], v[178:181], v[14:17], v[66:69]
	v_mul_f32_e32 v92, 0x3f317217, v4
	v_fma_f32 v92, v4, s53, -v92
	v_fmac_f32_e32 v92, 0x3377d1cf, v4
	v_fma_f32 v4, v4, s53, v92
	s_waitcnt lgkmcnt(1)
	v_mfma_f32_16x16x32_bf16 v[66:69], v[184:187], v[18:21], v[66:69]
	v_cmp_lt_i32_e32 vcc, v5, v90
	v_mul_f32_e64 v5, |v64|, s49
	v_exp_f32_e32 v5, v5
	v_add_f32_e32 v62, v62, v4
	v_cndmask_b32_e64 v4, 0, -v62, vcc
	v_sub_f32_e32 v62, v63, v62
	v_add_f32_e32 v5, 1.0, v5
	v_cndmask_b32_e32 v157, v149, v62, vcc
	v_mul_f32_e64 v92, |v65|, s49
	v_exp_f32_e32 v92, v92
	v_log_f32_e32 v5, v5
	v_max_f32_e32 v62, v64, v64
	v_max_f32_e32 v94, 0, v62
	s_waitcnt lgkmcnt(0)
	v_mfma_f32_16x16x32_bf16 v[66:69], v[188:191], v[22:25], v[66:69]
	v_mul_f32_e32 v62, 0x3f317217, v5
	v_fma_f32 v62, v5, s53, -v62
	v_fmac_f32_e32 v62, 0x3377d1cf, v5
	v_fma_f32 v5, v5, s53, v62
	v_or_b32_e32 v63, s18, v75
	s_nop 0
	v_mov_b32_e32 v96, v5
	v_add_f32_e32 v5, 1.0, v92
	v_max_f32_e32 v92, v65, v65
	v_max_f32_e32 v92, 0, v92
	v_log_f32_e32 v5, v5
	v_or_b32_e32 v62, s18, v99
	v_mul_f32_e32 v95, 0x3f317217, v5
	v_fma_f32 v95, v5, s53, -v95
	v_fmac_f32_e32 v95, 0x3377d1cf, v5
	v_fma_f32 v5, v5, s53, v95
	s_nop 1
	v_add_f32_e32 v5, v92, v5
	v_mul_f32_e64 v92, |v58|, s49
	v_exp_f32_e32 v92, v92
	v_cmp_lt_i32_e32 vcc, v62, v90
	v_max_f32_e32 v95, v58, v58
	v_max_f32_e32 v95, 0, v95
	v_cndmask_b32_e64 v62, 0, -v5, vcc
	v_sub_f32_e32 v5, v65, v5
	v_cndmask_b32_e32 v65, v149, v5, vcc
	v_add_f32_e32 v5, 1.0, v92
	s_nop 1
	v_log_f32_e32 v5, v5
	v_or_b32_e32 v92, s18, v100
	v_mul_f32_e32 v97, 0x3f317217, v5
	v_fma_f32 v97, v5, s53, -v97
	v_fmac_f32_e32 v97, 0x3377d1cf, v5
	v_fma_f32 v5, v5, s53, v97
	s_nop 1
	v_add_f32_e32 v5, v95, v5
	v_mul_f32_e64 v95, |v59|, s49
	v_exp_f32_e32 v95, v95
	v_sub_f32_e32 v58, v58, v5
	v_cmp_lt_i32_e32 vcc, v92, v90
	v_sub_f32_e32 v5, 0, v5
	s_nop 0
	v_cndmask_b32_e32 v163, v149, v58, vcc
	v_add_f32_e32 v58, 1.0, v95
	v_cndmask_b32_e32 v5, 0, v5, vcc
	v_max_f32_e32 v95, v59, v59
	v_max_f32_e32 v95, 0, v95
	v_log_f32_e32 v58, v58
	v_or_b32_e32 v92, s18, v101
; __device__ __forceinline__ void attn_phase(Frame& F, bf16* OZ) {
;     ...
;                 for (int sb = 0; sb < 4; ++sb) { tsum[sb] = 0.f;
; #pragma unroll
;                     for (int e = 0; e < 4; ++e) { const int s = 16 * sb + 4 * g4 + e; const float z = sc[sb][e]; const bool vis = (s < nvalid) && (spos0 + s < tpos);
;                         const float sp = fmaxf(z, 0.f) + __logf(1.0f + __expf(-fabsf(z)));
;                         lk[sb][e] = vis ? -sp : 0.f; sc[sb][e] = vis ? z - sp : -1e30f; tsum[sb] += lk[sb][e]; }
;                     const float v1 = __shfl_xor(tsum[sb], 16), v2 = __shfl_xor(tsum[sb], 32), v3 = __shfl_xor(tsum[sb], 48);
;                     above[sb] = ((g4 ^ 1) > g4 ? v1 : 0.f) + ((g4 ^ 2) > g4 ? v2 : 0.f) + ((g4 ^ 3) > g4 ? v3 : 0.f);
;                     ttot[sb] = (tsum[sb] + v1) + (v2 + v3); }
	v_mul_f32_e32 v97, 0x3f317217, v58
	v_fma_f32 v97, v58, s53, -v97
	v_fmac_f32_e32 v97, 0x3377d1cf, v58
	v_fma_f32 v58, v58, s53, v97
	s_nop 1
	v_add_f32_e32 v58, v95, v58
	v_mul_f32_e64 v95, |v60|, s49
	v_exp_f32_e32 v95, v95
	v_cmp_lt_i32_e32 vcc, v92, v90
	s_nop 1
	v_cndmask_b32_e64 v166, 0, -v58, vcc
	v_sub_f32_e32 v58, v59, v58
	v_cndmask_b32_e32 v167, v149, v58, vcc
	v_add_f32_e32 v58, 1.0, v95
	v_cmp_gt_f32_e32 vcc, s52, v58
	v_add_f32_e32 v5, v166, v5
	s_nop 0
	v_cndmask_b32_e64 v59, 0, 32, vcc
	v_ldexp_f32 v58, v58, v59
	v_log_f32_e32 v58, v58
	v_max_f32_e32 v59, v60, v60
	v_cndmask_b32_e32 v95, 0, v148, vcc
	v_max_f32_e32 v59, 0, v59
	v_mul_f32_e32 v92, 0x3f317217, v58
	v_fma_f32 v92, v58, s53, -v92
	v_fmac_f32_e32 v92, 0x3377d1cf, v58
	v_fmac_f32_e32 v92, 0x3f317217, v58
	v_cmp_lt_f32_e64 s[0:1], |v58|, s54
	s_nop 1
	v_cndmask_b32_e64 v58, v58, v92, s[0:1]
	v_mul_f32_e64 v92, |v61|, s49
	v_exp_f32_e32 v92, v92
	v_sub_f32_e32 v58, v58, v95
	v_add_f32_e32 v165, v59, v58
	v_sub_f32_e32 v168, v60, v165
	v_add_f32_e32 v58, 1.0, v92
	v_mul_f32_e64 v60, |v70|, s49
	v_exp_f32_e32 v60, v60
	v_log_f32_e32 v58, v58
	v_max_f32_e32 v59, v61, v61
	v_max_f32_e32 v95, 0, v59
	v_mul_f32_e32 v59, 0x3f317217, v58
	v_fma_f32 v59, v58, s53, -v59
	v_fmac_f32_e32 v59, 0x3377d1cf, v58
	v_fma_f32 v58, v58, s53, v59
	s_nop 1
	v_mov_b32_e32 v97, v58
	v_add_f32_e32 v58, 1.0, v60
	v_max_f32_e32 v60, v70, v70
	v_max_f32_e32 v60, 0, v60
	v_log_f32_e32 v58, v58
	v_or_b32_e32 v59, s18, v102
	v_mul_f32_e32 v92, 0x3f317217, v58
	v_fma_f32 v92, v58, s53, -v92
	v_fmac_f32_e32 v92, 0x3377d1cf, v58
	v_fma_f32 v58, v58, s53, v92
	s_nop 1
	v_add_f32_e32 v58, v60, v58
	v_sub_f32_e32 v60, v70, v58
	v_mul_f32_e64 v70, |v71|, s49
	v_exp_f32_e32 v70, v70
	v_cmp_lt_i32_e32 vcc, v59, v90
	v_sub_f32_e32 v58, 0, v58
	v_add_f32_e32 v59, 1.0, v70
	v_cndmask_b32_e32 v169, v149, v60, vcc
	v_cndmask_b32_e32 v58, 0, v58, vcc
	v_max_f32_e32 v70, v71, v71
	v_max_f32_e32 v70, 0, v70
	v_log_f32_e32 v59, v59
	v_or_b32_e32 v60, s18, v103
	v_mul_f32_e32 v92, 0x3f317217, v59
	v_fma_f32 v92, v59, s53, -v92
	v_fmac_f32_e32 v92, 0x3377d1cf, v59
	v_fma_f32 v59, v59, s53, v92
	s_nop 1
	v_cmp_lt_i32_e32 vcc, v60, v90
	v_mul_f32_e64 v60, |v72|, s49
	v_exp_f32_e32 v60, v60
	v_add_f32_e32 v59, v70, v59
	v_cndmask_b32_e64 v170, 0, -v59, vcc
	v_sub_f32_e32 v59, v71, v59
	v_cndmask_b32_e32 v171, v149, v59, vcc
	v_add_f32_e32 v59, 1.0, v60
	v_max_f32_e32 v70, v72, v72
	v_max_f32_e32 v70, 0, v70
	v_log_f32_e32 v59, v59
	v_or_b32_e32 v60, s18, v104
	v_add_f32_e32 v58, v170, v58
	v_mul_f32_e32 v71, 0x3f317217, v59
	v_fma_f32 v71, v59, s53, -v71
	v_fmac_f32_e32 v71, 0x3377d1cf, v59
	v_fma_f32 v59, v59, s53, v71
	s_nop 1
	v_cmp_lt_i32_e32 vcc, v60, v90
	v_mul_f32_e64 v60, |v73|, s49
	v_exp_f32_e32 v60, v60
	v_add_f32_e32 v59, v70, v59
	v_cndmask_b32_e64 v172, 0, -v59, vcc
	v_sub_f32_e32 v59, v72, v59
	v_cndmask_b32_e32 v173, v149, v59, vcc
	v_add_f32_e32 v59, 1.0, v60
	v_max_f32_e32 v70, v73, v73
	v_max_f32_e32 v70, 0, v70
	v_log_f32_e32 v59, v59
	v_or_b32_e32 v60, s18, v105
	v_add_f32_e32 v58, v172, v58
	v_mul_f32_e32 v71, 0x3f317217, v59
	v_fma_f32 v71, v59, s53, -v71
	v_fmac_f32_e32 v71, 0x3377d1cf, v59
	v_fma_f32 v59, v59, s53, v71
	s_nop 1
	v_add_f32_e32 v71, v70, v59
	v_cmp_lt_i32_e32 vcc, v60, v90
	v_sub_f32_e32 v60, v73, v71
	s_nop 0
	v_cndmask_b32_e64 v174, 0, -v71, vcc
	v_add_f32_e32 v58, v174, v58
	ds_bpermute_b32 v59, v154, v58
	ds_bpermute_b32 v70, v156, v58
	ds_bpermute_b32 v71, v155, v58
	v_cndmask_b32_e32 v175, v149, v60, vcc
	v_mul_f32_e64 v60, |v66|, s49
	v_exp_f32_e32 v60, v60
	s_waitcnt lgkmcnt(2)
	v_cndmask_b32_e64 v72, 0, v59, s[6:7]
	s_waitcnt lgkmcnt(0)
	v_pk_add_f32 v[58:59], v[58:59], v[70:71]
	v_cndmask_b32_e64 v92, 0, v71, s[8:9]
	v_pk_add_f32 v[58:59], v[58:59], v[58:59] op_sel_hi:[0,1]
	v_add_f32_e32 v58, 1.0, v60
	v_cndmask_b32_e64 v164, 0, v70, s[4:5]
	v_max_f32_e32 v70, v66, v66
	v_log_f32_e32 v58, v58
	v_max_f32_e32 v70, 0, v70
	v_or_b32_e32 v60, s18, v106
	v_mul_f32_e32 v71, 0x3f317217, v58
	v_fma_f32 v71, v58, s53, -v71
	v_fmac_f32_e32 v71, 0x3377d1cf, v58
	v_fma_f32 v58, v58, s53, v71
	s_nop 1
	v_add_f32_e32 v58, v70, v58
	v_mul_f32_e64 v70, |v67|, s49
	v_exp_f32_e32 v70, v70
	v_sub_f32_e32 v66, v66, v58
	v_cmp_lt_i32_e32 vcc, v60, v90
	v_sub_f32_e32 v58, 0, v58
	v_add_f32_e32 v60, 1.0, v70
	v_cndmask_b32_e32 v176, v149, v66, vcc
	v_cndmask_b32_e32 v58, 0, v58, vcc
	v_max_f32_e32 v70, v67, v67
	v_max_f32_e32 v70, 0, v70
	v_log_f32_e32 v60, v60
	v_or_b32_e32 v66, s18, v107
	v_mul_f32_e32 v71, 0x3f317217, v60
	v_fma_f32 v71, v60, s53, -v71
	v_fmac_f32_e32 v71, 0x3377d1cf, v60
	v_fma_f32 v60, v60, s53, v71
	s_nop 1
	v_cmp_lt_i32_e32 vcc, v66, v90
	v_mul_f32_e64 v66, |v68|, s49
	v_exp_f32_e32 v66, v66
	v_add_f32_e32 v60, v70, v60
	v_cndmask_b32_e64 v177, 0, -v60, vcc
	v_sub_f32_e32 v60, v67, v60
	v_add_f32_e32 v66, 1.0, v66
	v_cndmask_b32_e32 v60, v149, v60, vcc
	v_max_f32_e32 v70, v68, v68
	v_max_f32_e32 v70, 0, v70
	v_log_f32_e32 v66, v66
	v_or_b32_e32 v67, s18, v108
	v_add_f32_e32 v58, v177, v58
	v_mul_f32_e32 v71, 0x3f317217, v66
	v_fma_f32 v71, v66, s53, -v71
	v_fmac_f32_e32 v71, 0x3377d1cf, v66
	v_fma_f32 v66, v66, s53, v71
	s_nop 1
	v_cmp_lt_i32_e32 vcc, v67, v90
	v_mul_f32_e64 v67, |v69|, s49
	v_exp_f32_e32 v67, v67
	v_add_f32_e32 v66, v70, v66
	v_cndmask_b32_e64 v70, 0, -v66, vcc
	v_sub_f32_e32 v66, v68, v66
	v_cndmask_b32_e32 v71, v149, v66, vcc
	v_add_f32_e32 v66, 1.0, v67
	v_max_f32_e32 v68, v69, v69
	v_max_f32_e32 v68, 0, v68
	v_log_f32_e32 v66, v66
	v_or_b32_e32 v67, s18, v109
	v_add_f32_e32 v58, v70, v58
	v_cmp_lt_i32_e64 s[18:19], v158, v3
	v_mul_f32_e32 v73, 0x3f317217, v66
	v_fma_f32 v73, v66, s53, -v73
	v_fmac_f32_e32 v73, 0x3377d1cf, v66
	v_fma_f32 v66, v66, s53, v73
	s_nop 1
	v_add_f32_e32 v73, v68, v66
	v_cmp_lt_i32_e32 vcc, v67, v90
	v_cmp_lt_i32_e64 s[0:1], v162, v90
	s_nop 0
	v_cndmask_b32_e64 v178, 0, -v73, vcc
	v_add_f32_e32 v66, v178, v58
	ds_bpermute_b32 v67, v154, v66
	ds_bpermute_b32 v68, v156, v66
	v_sub_f32_e32 v58, v69, v73
	ds_bpermute_b32 v69, v155, v66
	v_cndmask_b32_e32 v58, v149, v58, vcc
	s_waitcnt lgkmcnt(2)
; __device__ __forceinline__ unsigned pk2(float lo, float hi) { const cvt_f2 v = {lo, hi}; const cvt_b2 r = __builtin_convertvector(v, cvt_b2); return __builtin_bit_cast(unsigned, r); }
; #define MFMA16(a, b, c) __builtin_amdgcn_mfma_f32_16x16x32_bf16((a), (b), (c), 0, 0, 0)
; __device__ __forceinline__ void attn_phase(Frame& F, bf16* OZ) {
;     ...
;                     const float v1 = __shfl_xor(tsum[sb], 16), v2 = __shfl_xor(tsum[sb], 32), v3 = __shfl_xor(tsum[sb], 48);
;                     above[sb] = ((g4 ^ 1) > g4 ? v1 : 0.f) + ((g4 ^ 2) > g4 ? v2 : 0.f) + ((g4 ^ 3) > g4 ? v3 : 0.f);
;                     ttot[sb] = (tsum[sb] + v1) + (v2 + v3); }
;                 float after = carry;
; #pragma unroll
;     ...
; #pragma unroll
;                     for (int e = 3; e >= 0; --e) { const float w = __expf(sc[sb][e] + run); run += lk[sb][e]; sc[sb][e] = w; }
;                     after += ttot[sb]; }
;                 carry = after;
; #pragma unroll
;                 for (int kk = 0; kk < 2; ++kk) { v4u pkd; pkd.x = pk2(sc[2 * kk][0], sc[2 * kk][1]); pkd.y = pk2(sc[2 * kk][2], sc[2 * kk][3]); pkd.z = pk2(sc[2 * kk + 1][0], sc[2 * kk + 1][1]); pkd.w = pk2(sc[2 * kk + 1][2], sc[2 * kk + 1][3]);
;                     const bf16x8 pf = __builtin_bit_cast(bf16x8, pkd);
; #pragma unroll
;                     for (int dh = 0; dh < 2; ++dh) { unsigned aa[4]; bf16x8 vf[4];
; #pragma unroll
;                         for (int i = 0; i < 4; ++i) aa[i] = F.lds0 + VS + (32 * kk + 4 * g4 + q) * ST_ + (32 * (2 * dh + (i >> 1)) + 8 * p + 4 * (i & 1)) * 2;
;                         tr_read_x4(aa, 16 * ST_, vf);
; #pragma unroll
;                         for (int i = 0; i < 4; ++i) oacc[4 * dh + i] = MFMA16(vf[i], pf, oacc[4 * dh + i]); } }
;                 done = __all(carry < ATT_THR);
	v_cndmask_b32_e64 v73, 0, v67, s[6:7]
	s_waitcnt lgkmcnt(1)
	v_cndmask_b32_e64 v179, 0, v68, s[4:5]
	v_add_f32_e32 v73, v179, v73
	s_waitcnt lgkmcnt(0)
	v_cndmask_b32_e64 v179, 0, v69, s[8:9]
	v_add_f32_e32 v73, v73, v179
	v_pk_add_f32 v[66:67], v[66:67], v[68:69]
	v_add_f32_e32 v68, v93, v73
	v_add_f32_e32 v58, v58, v68
	v_mul_f32_e32 v58, 0x3fb8aa3b, v58
	v_exp_f32_e32 v179, v58
	v_add_f32_e32 v58, v178, v68
	v_add_f32_e32 v68, v71, v58
	v_mul_f32_e32 v68, 0x3fb8aa3b, v68
	v_cmp_lt_i32_e32 vcc, v159, v90
	v_exp_f32_e32 v178, v68
	v_add_f32_e32 v180, v70, v58
	v_cndmask_b32_e32 v159, v149, v161, vcc
	v_pk_add_f32 v[68:69], v[94:95], v[96:97]
	v_cndmask_b32_e64 v71, 0, -v165, s[18:19]
	v_cndmask_b32_e32 v70, 0, v160, vcc
	v_cmp_lt_i32_e32 vcc, v63, v3
	v_pk_add_f32 v[94:95], v[70:71], v[4:5]
	v_cndmask_b32_e64 v96, 0, -v68, s[0:1]
	v_cndmask_b32_e64 v97, 0, -v69, vcc
	v_pk_add_f32 v[94:95], v[96:97], v[94:95]
	ds_bpermute_b32 v63, v156, v95
	v_mov_b32_e32 v165, v66
	v_mov_b32_e32 v73, v67
	v_add_f32_e32 v58, v60, v180
	v_pk_add_f32 v[66:67], v[164:165], v[72:73]
	v_mul_f32_e32 v58, 0x3fb8aa3b, v58
	v_pk_add_f32 v[66:67], v[66:67], v[92:93]
	ds_bpermute_b32 v92, v154, v95
	v_exp_f32_e32 v181, v58
	v_sub_f32_e32 v58, v64, v68
	s_waitcnt lgkmcnt(1)
	v_pk_add_f32 v[72:73], v[62:63], v[94:95]
	v_sub_f32_e32 v61, v61, v69
	ds_bpermute_b32 v69, v155, v95
	v_cndmask_b32_e64 v64, v149, v58, s[0:1]
	ds_bpermute_b32 v60, v156, v72
	ds_bpermute_b32 v58, v154, v72
	v_add_f32_e32 v5, v66, v67
	ds_bpermute_b32 v66, v155, v72
	v_cndmask_b32_e32 v93, v149, v61, vcc
	v_cndmask_b32_e64 v61, 0, v63, s[4:5]
	s_waitcnt lgkmcnt(4)
	v_cndmask_b32_e64 v63, 0, v92, s[6:7]
	v_add_f32_e32 v61, v61, v63
	s_waitcnt lgkmcnt(3)
	v_cndmask_b32_e64 v63, 0, v69, s[8:9]
	s_waitcnt lgkmcnt(2)
	v_cndmask_b32_e64 v68, 0, v60, s[4:5]
	s_waitcnt lgkmcnt(1)
	v_cndmask_b32_e64 v70, 0, v58, s[6:7]
	v_add_f32_e32 v63, v61, v63
	v_add_f32_e32 v61, v92, v69
	v_add_f32_e32 v68, v68, v70
	s_waitcnt lgkmcnt(0)
	v_cndmask_b32_e64 v70, 0, v66, s[8:9]
	v_pk_add_f32 v[60:61], v[72:73], v[60:61]
	v_pk_add_f32 v[58:59], v[58:59], v[66:67]
	v_add_f32_e32 v68, v68, v70
	v_pk_add_f32 v[154:155], v[60:61], v[58:59]
	v_add_f32_e32 v63, v63, v59
	v_add_f32_e32 v58, v68, v155
	v_cndmask_b32_e64 v70, v149, v168, s[18:19]
	v_add_f32_e32 v66, v93, v63
	v_add_f32_e32 v63, v97, v63
	v_add_f32_e32 v59, v65, v58
	v_add_f32_e32 v58, v62, v58
	v_add_f32_e32 v67, v70, v63
	v_add_f32_e32 v63, v71, v63
	v_add_f32_e32 v60, v64, v58
	v_add_f32_e32 v58, v96, v58
	v_add_f32_e32 v69, v167, v63
	v_add_f32_e32 v63, v166, v63
	v_add_f32_e32 v4, v4, v58
	v_add_f32_e32 v63, v163, v63
	v_add_f32_e32 v61, v157, v58
	v_add_f32_e32 v4, v159, v4
	v_mul_f32_e32 v66, 0x3fb8aa3b, v66
	v_mul_f32_e32 v67, 0x3fb8aa3b, v67
	v_mul_f32_e32 v69, 0x3fb8aa3b, v69
	v_mul_f32_e32 v63, 0x3fb8aa3b, v63
	v_mul_f32_e32 v59, 0x3fb8aa3b, v59
	v_mul_f32_e32 v60, 0x3fb8aa3b, v60
	v_mul_f32_e32 v61, 0x3fb8aa3b, v61
	v_mul_f32_e32 v4, 0x3fb8aa3b, v4
	v_exp_f32_e32 v66, v66
	v_exp_f32_e32 v69, v69
	v_exp_f32_e32 v59, v59
	v_exp_f32_e32 v61, v61
	v_exp_f32_e32 v4, v4
	v_exp_f32_e32 v60, v60
	v_exp_f32_e32 v62, v63
	v_exp_f32_e32 v63, v67
	v_cvt_pk_bf16_f32 v58, v4, v61
	v_cvt_pk_bf16_f32 v59, v60, v59
	v_cvt_pk_bf16_f32 v60, v62, v69
	v_cvt_pk_bf16_f32 v61, v63, v66
	ds_read_b64_tr_b16 v[92:93], v110
	ds_read_b64_tr_b16 v[94:95], v114
	ds_read_b64_tr_b16 v[70:71], v111
	ds_read_b64_tr_b16 v[72:73], v115
	ds_read_b64_tr_b16 v[66:67], v112
	ds_read_b64_tr_b16 v[68:69], v116
	ds_read_b64_tr_b16 v[62:63], v113
	ds_read_b64_tr_b16 v[64:65], v117
	s_waitcnt lgkmcnt(0)
	v_add_f32_e32 v156, v177, v180
	v_add_f32_e32 v4, v176, v156
	v_mfma_f32_16x16x32_bf16 v[54:57], v[92:95], v[58:61], v[54:57]
	v_add_f32_e32 v92, v175, v5
	v_add_f32_e32 v5, v174, v5
	v_mul_f32_e32 v4, 0x3fb8aa3b, v4
	v_mfma_f32_16x16x32_bf16 v[50:53], v[70:73], v[58:61], v[50:53]
	v_mul_f32_e32 v70, 0x3fb8aa3b, v92
	v_exp_f32_e32 v96, v70
	v_exp_f32_e32 v4, v4
	v_mfma_f32_16x16x32_bf16 v[46:49], v[66:69], v[58:61], v[46:49]
	v_add_f32_e32 v66, v173, v5
	v_mul_f32_e32 v97, 0x3fb8aa3b, v66
	v_add_f32_e32 v5, v172, v5
	v_mfma_f32_16x16x32_bf16 v[42:45], v[62:65], v[58:61], v[42:45]
	ds_read_b64_tr_b16 v[92:93], v118
	ds_read_b64_tr_b16 v[94:95], v122
	ds_read_b64_tr_b16 v[70:71], v119
	ds_read_b64_tr_b16 v[72:73], v123
	ds_read_b64_tr_b16 v[66:67], v120
	ds_read_b64_tr_b16 v[68:69], v124
	ds_read_b64_tr_b16 v[62:63], v121
	ds_read_b64_tr_b16 v[64:65], v125
	s_waitcnt lgkmcnt(0)
	s_nop 0
	v_mfma_f32_16x16x32_bf16 v[38:41], v[92:95], v[58:61], v[38:41]
	v_add_f32_e32 v92, v171, v5
	v_add_f32_e32 v5, v170, v5
	v_add_f32_e32 v5, v169, v5
	v_mul_f32_e32 v92, 0x3fb8aa3b, v92
	v_mul_f32_e32 v5, 0x3fb8aa3b, v5
	v_exp_f32_e32 v92, v92
	v_mfma_f32_16x16x32_bf16 v[30:33], v[66:69], v[58:61], v[30:33]
	v_exp_f32_e32 v5, v5
	v_exp_f32_e32 v66, v97
	v_mfma_f32_16x16x32_bf16 v[34:37], v[70:73], v[58:61], v[34:37]
	v_mfma_f32_16x16x32_bf16 v[26:29], v[62:65], v[58:61], v[26:29]
	v_cvt_pk_bf16_f32 v58, v5, v92
	v_cvt_pk_bf16_f32 v59, v66, v96
	v_cvt_pk_bf16_f32 v60, v4, v181
	v_cvt_pk_bf16_f32 v61, v178, v179
	ds_read_b64_tr_b16 v[92:93], v126
	ds_read_b64_tr_b16 v[94:95], v130
	ds_read_b64_tr_b16 v[70:71], v127
	ds_read_b64_tr_b16 v[72:73], v131
	ds_read_b64_tr_b16 v[66:67], v128
	ds_read_b64_tr_b16 v[68:69], v132
	ds_read_b64_tr_b16 v[62:63], v129
	ds_read_b64_tr_b16 v[64:65], v133
	s_waitcnt lgkmcnt(0)
	s_nop 1
	v_mfma_f32_16x16x32_bf16 v[54:57], v[92:95], v[58:61], v[54:57]
	v_mfma_f32_16x16x32_bf16 v[50:53], v[70:73], v[58:61], v[50:53]
	v_mfma_f32_16x16x32_bf16 v[46:49], v[66:69], v[58:61], v[46:49]
	v_mfma_f32_16x16x32_bf16 v[42:45], v[62:65], v[58:61], v[42:45]
	ds_read_b64_tr_b16 v[92:93], v134
	ds_read_b64_tr_b16 v[94:95], v138
	ds_read_b64_tr_b16 v[70:71], v135
	ds_read_b64_tr_b16 v[72:73], v139
	ds_read_b64_tr_b16 v[66:67], v136
	ds_read_b64_tr_b16 v[68:69], v140
	ds_read_b64_tr_b16 v[62:63], v137
	ds_read_b64_tr_b16 v[64:65], v141
	s_waitcnt lgkmcnt(0)
	s_nop 0
	v_mfma_f32_16x16x32_bf16 v[38:41], v[92:95], v[58:61], v[38:41]
	v_add_f32_e32 v93, v154, v155
	v_cmp_gt_f32_e32 vcc, s55, v93
	s_cmp_eq_u64 vcc, exec
	v_mfma_f32_16x16x32_bf16 v[34:37], v[70:73], v[58:61], v[34:37]
	s_cselect_b64 s[0:1], -1, 0
	s_mov_b64 s[64:65], s[0:1]
	v_mfma_f32_16x16x32_bf16 v[30:33], v[66:69], v[58:61], v[30:33]
	v_mfma_f32_16x16x32_bf16 v[26:29], v[62:65], v[58:61], v[26:29]
	s_and_saveexec_b64 s[18:19], s[10:11]
	s_cbranch_execz .LBB0_1905
	s_branch .LBB0_1913
